# code placement: the five hot loop heads (three GEMM K loops, two attention loops) pinned to 64-byte boundaries with .p2align 6
# baseline (speedup 1.0000x reference)
.Lfw_0:
	.p2align 6

.LBB0_716:
	s_or_b64 exec, exec, s[8:9]
	s_waitcnt vmcnt(4)
	v_mul_u32_u24_e32 v0, 0xd0, v33
	v_add3_u32 v227, 0, v0, v196
	s_waitcnt lgkmcnt(0)
	s_barrier
	ds_read_b128 v[0:3], v227
	s_waitcnt vmcnt(1)
	ds_read_b128 v[4:7], v227 offset:32
	s_waitcnt vmcnt(0) lgkmcnt(1)
	v_mfma_f32_32x32x16_bf16 v[16:31], v[0:3], v[112:115], 0
	ds_read_b128 v[0:3], v227 offset:6656
	ds_read_b128 v[8:11], v227 offset:6688
	v_lshlrev_b32_e32 v228, 2, v32
	v_or_b32_e32 v229, s12, v33
	s_and_b32 s7, s1, 7
	s_lshl_b32 s36, s7, 7
	s_lshl_b32 s7, s11, 2
	s_mov_b32 s60, 0
	s_waitcnt lgkmcnt(1)
	v_mfma_f32_32x32x16_bf16 v[34:49], v[0:3], v[112:115], 0
	s_movk_i32 s8, 0xc0
	s_lshl_b32 s11, s2, 8
	s_mov_b32 s61, s60
	s_mov_b32 s62, s60
	s_mov_b32 s63, s60
	s_mov_b32 s64, s60
	s_mov_b32 s65, s60
	v_mfma_f32_32x32x16_bf16 v[16:31], v[4:7], v[116:119], v[16:31]
	ds_read_b128 v[0:3], v227 offset:64
	ds_read_b128 v[4:7], v227 offset:96
	s_mov_b32 s66, s60
	s_mov_b32 s67, s60
	s_mov_b32 s68, s60
	s_mov_b32 s69, s60
	s_mov_b32 s70, s60
	s_mov_b32 s71, s60
	s_waitcnt lgkmcnt(2)
	v_mfma_f32_32x32x16_bf16 v[34:49], v[8:11], v[116:119], v[34:49]
	s_mov_b32 s72, s60
	s_mov_b32 s73, s60
	s_mov_b32 s74, s60
	s_mov_b32 s75, s60
	v_mov_b32_e32 v138, v197
	v_mov_b32_e32 v139, v197
	v_mov_b32_e32 v136, v197
	s_waitcnt lgkmcnt(1)
	v_mfma_f32_32x32x16_bf16 v[16:31], v[0:3], v[120:123], v[16:31]
	ds_read_b128 v[0:3], v227 offset:6720
	ds_read_b128 v[8:11], v227 offset:6752
	v_mov_b32_e32 v137, v197
	v_mov_b64_e32 v[154:155], v[138:139]
	v_ashrrev_i32_e32 v205, 31, v204
	s_add_i32 s15, s7, 4
	v_add_u32_e32 v231, 0, v51
	v_lshlrev_b32_e32 v212, 2, v54
	s_waitcnt lgkmcnt(1)
	v_mfma_f32_32x32x16_bf16 v[34:49], v[0:3], v[120:123], v[34:49]
	ds_read_b128 v[0:3], v227 offset:128
	v_mov_b32_e32 v213, v197
	v_lshlrev_b32_e32 v214, 3, v52
	v_mov_b32_e32 v215, v197
	v_lshlrev_b32_e32 v216, 2, v52
	v_mov_b32_e32 v217, v197
	v_mul_hi_u32_u24_e32 v219, 6, v54
	v_mfma_f32_32x32x16_bf16 v[16:31], v[4:7], v[124:127], v[16:31]
	v_lshrrev_b32_e32 v4, 2, v50
	v_and_or_b32 v33, v4, 3, v228
	v_lshlrev_b32_e32 v4, 1, v50
	v_and_b32_e32 v53, 32, v4
	v_lshlrev_b32_e32 v4, 3, v50
	v_and_b32_e32 v55, 24, v4
	v_mul_u32_u24_e32 v218, 6, v54
	s_waitcnt lgkmcnt(1)
	v_mfma_f32_32x32x16_bf16 v[34:49], v[8:11], v[124:127], v[34:49]
	ds_read_b128 v[4:7], v227 offset:6784
	ds_read_b128 v[8:11], v227 offset:160
	ds_read_b128 v[58:61], v227 offset:6816
	v_mul_hi_u32_u24_e32 v221, 6, v52
	v_mul_u32_u24_e32 v220, 6, v52
	v_mov_b32_e32 v234, 0
	v_mov_b64_e32 v[152:153], v[136:137]
	s_waitcnt lgkmcnt(0)
	v_mfma_f32_32x32x16_bf16 v[16:31], v[0:3], v[128:131], v[16:31]
	s_barrier
	v_mfma_f32_32x32x16_bf16 v[34:49], v[4:7], v[128:131], v[34:49]
	v_mfma_f32_32x32x16_bf16 v[16:31], v[8:11], v[132:135], v[16:31]
	v_mov_b64_e32 v[0:1], s[60:61]
	v_mov_b64_e32 v[14:15], s[74:75]
	v_mov_b64_e32 v[2:3], s[62:63]
	v_mov_b64_e32 v[4:5], s[64:65]
	v_mov_b64_e32 v[6:7], s[66:67]
	v_mov_b64_e32 v[8:9], s[68:69]
	v_mov_b64_e32 v[10:11], s[70:71]
	v_mfma_f32_32x32x16_bf16 v[34:49], v[58:61], v[132:135], v[34:49]
	s_nop 3
	v_max_f32_e32 v32, v17, v17
	v_max_f32_e32 v62, v16, v16
	v_max_f32_e32 v32, v62, v32
	v_mov_b64_e32 v[12:13], s[72:73]
	s_nop 3
	v_max3_f32 v58, v18, v19, v35
	v_max3_f32 v32, v32, v34, v36
	v_max3_f32 v32, v32, v37, v20
	v_max3_f32 v58, v58, v22, v23
	v_max3_f32 v32, v32, v21, v38
	v_max3_f32 v58, v58, v40, v41
	v_max3_f32 v32, v32, v39, v24
	v_max3_f32 v58, v58, v26, v27
	v_max3_f32 v32, v32, v25, v42
	v_max3_f32 v58, v58, v44, v45
	v_max3_f32 v32, v32, v43, v28
	v_max3_f32 v58, v58, v30, v31
	v_max3_f32 v32, v32, v29, v46
	v_max3_f32 v58, v58, v48, v49
	v_max3_f32 v32, v32, v47, v58
	v_mov_b32_e32 v58, v32
	s_nop 1
	v_permlane32_swap_b32_e32 v32, v58
	v_max_f32_e32 v58, v58, v58
	v_max_f32_e32 v32, v32, v32
	v_max_f32_e32 v230, v32, v58
	v_sub_f32_e32 v66, v18, v230
	v_sub_f32_e32 v64, v16, v230
	v_mad_u32_u24 v16, v33, s8, 0
	s_add_i32 s8, s11, 0xffffc140
	v_and_b32_e32 v18, 7, v50
	v_sub_f32_e32 v65, v17, v230
	v_add3_u32 v232, v16, v53, v55
	v_or_b32_e32 v233, s8, v228
	v_lshl_add_u64 v[16:17], v[56:57], 0, s[36:37]
	v_lshlrev_b32_e32 v196, 4, v18
	v_readlane_b32 s8, v250, 20
	v_lshl_add_u64 v[16:17], v[16:17], 0, v[196:197]
	v_readlane_b32 s9, v250, 21
	v_xor_b32_e32 v32, 0x80000000, v230
	v_sub_f32_e32 v79, v31, v230
	v_sub_f32_e32 v78, v30, v230
	v_sub_f32_e32 v77, v29, v230
	v_sub_f32_e32 v76, v28, v230
	v_sub_f32_e32 v75, v27, v230
	v_sub_f32_e32 v74, v26, v230
	v_sub_f32_e32 v73, v25, v230
	v_sub_f32_e32 v72, v24, v230
	v_sub_f32_e32 v71, v23, v230
	v_sub_f32_e32 v70, v22, v230
	v_sub_f32_e32 v69, v21, v230
	v_sub_f32_e32 v68, v20, v230
	v_sub_f32_e32 v67, v19, v230
	v_lshl_add_u64 v[210:211], s[8:9], 0, v[16:17]
	v_mov_b64_e32 v[30:31], v[14:15]
	v_sub_f32_e32 v111, v49, v230
	v_sub_f32_e32 v110, v48, v230
	v_sub_f32_e32 v109, v47, v230
	v_sub_f32_e32 v108, v46, v230
	v_sub_f32_e32 v107, v45, v230
	v_sub_f32_e32 v106, v44, v230
	v_sub_f32_e32 v105, v43, v230
	v_sub_f32_e32 v104, v42, v230
	v_sub_f32_e32 v103, v41, v230
	v_sub_f32_e32 v102, v40, v230
	v_sub_f32_e32 v101, v39, v230
	v_sub_f32_e32 v100, v38, v230
	v_sub_f32_e32 v99, v37, v230
	v_sub_f32_e32 v98, v36, v230
	v_sub_f32_e32 v97, v35, v230
	v_sub_f32_e32 v96, v34, v230
	v_lshlrev_b32_e32 v196, 3, v54
	v_mov_b32_e32 v48, 0
	v_mov_b64_e32 v[28:29], v[12:13]
	v_mov_b64_e32 v[26:27], v[10:11]
	v_mov_b64_e32 v[24:25], v[8:9]
	v_mov_b64_e32 v[22:23], v[6:7]
	v_mov_b64_e32 v[20:21], v[4:5]
	v_mov_b64_e32 v[18:19], v[2:3]
	v_mov_b64_e32 v[16:17], v[0:1]
	v_mov_b32_e32 v33, v32
	v_mov_b32_e32 v34, v32
	v_mov_b32_e32 v35, v32
	v_mov_b32_e32 v36, v32
	v_mov_b32_e32 v37, v32
	v_mov_b32_e32 v38, v32
	v_mov_b32_e32 v39, v32
	v_mov_b32_e32 v40, v32
	v_mov_b32_e32 v41, v32
	v_mov_b32_e32 v42, v32
	v_mov_b32_e32 v43, v32
	v_mov_b32_e32 v44, v32
	v_mov_b32_e32 v45, v32
	v_mov_b32_e32 v46, v32
	v_mov_b32_e32 v47, v32
	.p2align 6

.LBB0_762:
	s_nop 7
	v_max_f32_e32 v32, v1, v1
	v_max_f32_e32 v33, v0, v0
	v_max_f32_e32 v32, v33, v32
	v_max3_f32 v33, v2, v3, v17
	v_max3_f32 v32, v32, v16, v18
	v_max3_f32 v32, v32, v19, v4
	v_max3_f32 v33, v33, v6, v7
	v_max3_f32 v32, v32, v5, v20
	v_max3_f32 v33, v33, v22, v23
	v_max3_f32 v32, v32, v21, v8
	v_max3_f32 v33, v33, v10, v11
	v_max3_f32 v32, v32, v9, v24
	v_max3_f32 v33, v33, v26, v27
	v_max3_f32 v32, v32, v25, v12
	v_max3_f32 v33, v33, v14, v15
	v_max3_f32 v32, v32, v13, v28
	v_max3_f32 v33, v33, v30, v31
	v_max3_f32 v32, v32, v29, v33
	v_mov_b32_e32 v33, v32
	s_nop 1
	v_permlane32_swap_b32_e32 v32, v33
	s_cmp_lt_i32 s2, 0
	s_barrier
	s_cbranch_scc1 .LBB0_702
	v_lshrrev_b32_e32 v35, 2, v34
	v_max_f32_e32 v32, v32, v32
	v_max_f32_e32 v33, v33, v33
	v_and_or_b32 v35, v35, 3, v226
	v_lshlrev_b32_e32 v37, 1, v34
	v_lshlrev_b32_e32 v39, 3, v34
	v_max_f32_e32 v230, v32, v33
	s_movk_i32 s8, 0xc0
	v_and_b32_e32 v37, 32, v37
	v_and_b32_e32 v39, 24, v39
	v_sub_f32_e32 v64, v0, v230
	v_mad_u32_u24 v0, v35, s8, 0
	v_sub_f32_e32 v66, v2, v230
	v_add3_u32 v231, v0, v37, v39
	v_subrev_u32_e32 v0, s11, v226
	v_and_b32_e32 v2, 7, v34
	v_sub_f32_e32 v65, v1, v230
	v_add_u32_e32 v232, 0x60, v0
	v_lshl_add_u64 v[0:1], v[40:41], 0, s[36:37]
	v_lshlrev_b32_e32 v196, 4, v2
	v_readlane_b32 s8, v250, 20
	v_sub_f32_e32 v79, v15, v230
	v_sub_f32_e32 v78, v14, v230
	v_lshl_add_u64 v[0:1], v[0:1], 0, v[196:197]
	v_readlane_b32 s9, v250, 21
	v_mov_b32_e32 v14, v197
	v_mov_b32_e32 v15, v197
	v_mov_b32_e32 v138, v197
	v_mov_b32_e32 v139, v197
	s_lshl_b32 s2, s2, 2
	v_xor_b32_e32 v32, 0x80000000, v230
	v_sub_f32_e32 v111, v31, v230
	v_sub_f32_e32 v110, v30, v230
	v_sub_f32_e32 v109, v29, v230
	v_sub_f32_e32 v108, v28, v230
	v_sub_f32_e32 v107, v27, v230
	v_sub_f32_e32 v106, v26, v230
	v_sub_f32_e32 v105, v25, v230
	v_sub_f32_e32 v104, v24, v230
	v_sub_f32_e32 v103, v23, v230
	v_sub_f32_e32 v102, v22, v230
	v_sub_f32_e32 v101, v21, v230
	v_sub_f32_e32 v100, v20, v230
	v_sub_f32_e32 v99, v19, v230
	v_sub_f32_e32 v98, v18, v230
	v_sub_f32_e32 v97, v17, v230
	v_sub_f32_e32 v96, v16, v230
	v_sub_f32_e32 v77, v13, v230
	v_sub_f32_e32 v76, v12, v230
	v_sub_f32_e32 v75, v11, v230
	v_sub_f32_e32 v74, v10, v230
	v_sub_f32_e32 v73, v9, v230
	v_sub_f32_e32 v72, v8, v230
	v_sub_f32_e32 v71, v7, v230
	v_sub_f32_e32 v70, v6, v230
	v_sub_f32_e32 v69, v5, v230
	v_sub_f32_e32 v68, v4, v230
	v_sub_f32_e32 v67, v3, v230
	v_lshl_add_u64 v[210:211], s[8:9], 0, v[0:1]
	v_mov_b32_e32 v0, v197
	v_mov_b32_e32 v1, v197
	v_mov_b32_e32 v2, v197
	v_mov_b32_e32 v3, v197
	v_mov_b32_e32 v4, v197
	v_mov_b32_e32 v5, v197
	v_mov_b32_e32 v6, v197
	v_mov_b32_e32 v7, v197
	v_mov_b32_e32 v8, v197
	v_mov_b32_e32 v9, v197
	v_mov_b32_e32 v10, v197
	v_mov_b32_e32 v11, v197
	v_mov_b32_e32 v12, v197
	v_mov_b32_e32 v13, v197
	v_mov_b32_e32 v136, v197
	v_mov_b32_e32 v137, v197
	v_mov_b64_e32 v[154:155], v[138:139]
	v_mov_b64_e32 v[30:31], v[14:15]
	s_add_i32 s7, s2, 4
	v_lshlrev_b32_e32 v196, 3, v38
	v_lshlrev_b32_e32 v212, 2, v38
	v_mov_b32_e32 v213, v197
	v_lshlrev_b32_e32 v214, 3, v36
	v_mov_b32_e32 v215, v197
	v_lshlrev_b32_e32 v216, 2, v36
	v_mov_b32_e32 v217, v197
	v_mul_hi_u32_u24_e32 v219, 6, v38
	v_mul_u32_u24_e32 v218, 6, v38
	v_mul_hi_u32_u24_e32 v221, 6, v36
	v_mul_u32_u24_e32 v220, 6, v36
	s_mov_b32 s15, 0
	v_mov_b32_e32 v233, 0
	v_mov_b64_e32 v[152:153], v[136:137]
	v_mov_b32_e32 v48, 0
	v_mov_b64_e32 v[28:29], v[12:13]
	v_mov_b64_e32 v[26:27], v[10:11]
	v_mov_b64_e32 v[24:25], v[8:9]
	v_mov_b64_e32 v[22:23], v[6:7]
	v_mov_b64_e32 v[20:21], v[4:5]
	v_mov_b64_e32 v[18:19], v[2:3]
	v_mov_b64_e32 v[16:17], v[0:1]
	v_mov_b32_e32 v33, v32
	v_mov_b32_e32 v34, v32
	v_mov_b32_e32 v35, v32
	v_mov_b32_e32 v36, v32
	v_mov_b32_e32 v37, v32
	v_mov_b32_e32 v38, v32
	v_mov_b32_e32 v39, v32
	v_mov_b32_e32 v40, v32
	v_mov_b32_e32 v41, v32
	v_mov_b32_e32 v42, v32
	v_mov_b32_e32 v43, v32
	v_mov_b32_e32 v44, v32
	v_mov_b32_e32 v45, v32
	v_mov_b32_e32 v46, v32
	v_mov_b32_e32 v47, v32
	.p2align 6
